# grid barrier: arrivals sharded over 16 counters (blk mod 16) polled by a 16-lane load, instead of 256 atomics on one word
# speedup vs baseline: 1.0257x; 1.0238x over previous
; #define LAS __attribute__((address_space(3)))
; DI int opq0() { int z = 0; asm volatile("" : "+s"(z)); return z; }
;     DI bool next(int i, Unit& u) const {
;         const long L = (long)base + (long)i * G + c; if (L >= nwg) return false;
;         const int z = (int)(L / per); int wgid = (int)(L % per);
;         if (per >= 64) { const int q = per / NXCD, r = per % NXCD, xcd = wgid % NXCD, off = wgid / NXCD; wgid = (xcd < r ? xcd * (q + 1) : r * (q + 1) + (xcd - r) * q) + off; }
;         const int nig = WGM * nN, gid = wgid / nig, fm = gid * WGM, gsz = (nM - fm) < WGM ? (nM - fm) : WGM;
;         u.pm = fm + ((wgid % nig) % gsz); u.pn = (wgid % nig) / gsz; u.z = z; return true;
; __global__ void __launch_bounds__(512, 2) mega(Params P) {
;     extern __shared__ __attribute__((aligned(16))) unsigned char smem_raw[];
;     LAS unsigned char* lds = (LAS unsigned char*)smem_raw;
;     cg::grid_group grid = cg::this_grid();
;     const int G = gridDim.x, blk = blockIdx.x;
;     Sched S;
;     ...
;     for (int layer = 0; layer < DEPTH; ++layer) {
;         { TID_VARS; if (layer == 0 && tid == 0) *(volatile LAS unsigned*)(lds + 131072) = 0u; if (layer == 0 && blk == 0) { unsigned* bw = (unsigned*)(P.ws + opq0() + WS_BAR); for (int i = tid; i < 4096; i += 512) bw[i] = 0u; } phase_prep(P, layer, blk * 512 + tid, G * 512); }
_Z4mega6Params:
	v_writelane_b32 v255, s2, 9
	s_mov_b64 s[66:67], s[0:1]
	s_sub_i32 s0, s2, 48
	s_lshr_b32 s1, s0, 2
	s_mul_hi_u32 s1, s1, 0x1bacf915
	s_lshr_b32 s1, s1, 2
	s_mulk_i32 s1, 0x94
	s_sub_i32 s0, s0, s1
	s_cmpk_lt_i32 s2, 0x6c
	s_cselect_b32 s10, 0, 8
	s_add_i32 s1, s2, 0xffffff9c
	s_mov_b32 s70, s2
	s_cmpk_lt_i32 s2, 0x6c
	s_cselect_b32 s12, 8, 0x200
	s_cselect_b32 s2, 8, 0x94
	s_cselect_b32 s14, s1, s0
	s_add_i32 s0, s70, 40
	s_mul_hi_i32 s1, s0, 0xdd67c8a7
	v_writelane_b32 v253, s2, 0
	s_add_i32 s1, s1, s0
	s_load_dword s58, s[66:67], 0xd8
	s_load_dwordx4 s[20:23], s[66:67], 0xc8
	v_writelane_b32 v253, s3, 1
	s_lshr_b32 s2, s1, 31
	s_ashr_i32 s1, s1, 7
	s_add_i32 s1, s1, s2
	s_mulk_i32 s1, 0x94
	s_sub_i32 s0, s0, s1
	s_cmpk_lt_i32 s70, 0x6c
	s_cselect_b32 s74, 0, 0x180
	s_cselect_b32 s80, 0, s0
	s_add_u32 s0, s66, 0xd8
	s_addc_u32 s1, s67, 0
	s_waitcnt lgkmcnt(0)
	s_ashr_i32 s59, s58, 31
	v_writelane_b32 v253, s0, 2
	s_cmp_lg_u64 s[58:59], 0x100
	s_cselect_b64 s[82:83], -1, 0
	v_writelane_b32 v253, s1, 3
	s_lshl_b32 s0, s70, 9
	v_writelane_b32 v253, s0, 4
	s_lshl_b32 s84, s58, 9
	s_lshl_b32 s16, s70, 3
	s_lshl_b32 s34, s58, 3
	s_lshl_b32 s0, s70, 6
	s_add_i32 s2, s58, s70
	s_cmpk_gt_i32 s70, 0x63
	v_writelane_b32 v253, s0, 5
	s_cselect_b64 s[0:1], -1, 0
	v_writelane_b32 v253, s0, 6
	s_cmpk_gt_u32 s70, 0x9b
	s_mov_b32 s94, 0
	v_writelane_b32 v253, s1, 7
	s_cselect_b64 s[0:1], -1, 0
	v_writelane_b32 v253, s0, 8
	s_ashr_i32 s81, s80, 31
	s_add_i32 s6, s70, 0xc0
	v_writelane_b32 v253, s1, 9
	s_add_i32 s0, s16, 0xfffffb20
	v_writelane_b32 v253, s0, 10
	s_bfe_u32 s0, s80, 0x3001c
	s_add_i32 s0, s80, s0
	s_sext_i32_i16 s1, s0
	s_and_b32 s0, s0, 0xfff8
	s_sub_i32 s4, s80, s0
	s_lshl_b32 s0, s70, 2
	s_ashr_i32 s3, s1, 3
	s_and_b32 s0, s0, 28
	s_ashr_i32 s1, s70, 6
	s_add_i32 s7, s0, s1
	s_add_i32 s0, s70, 64
	s_mul_hi_i32 s1, s0, 0x66666667
	s_lshr_b32 s8, s1, 31
	s_ashr_i32 s1, s1, 6
	s_add_i32 s1, s1, s8
	s_mulk_i32 s1, 0xa0
	s_bfe_u32 s71, s70, 0x30003
	s_sub_i32 s8, s0, s1
	s_cmpk_lt_i32 s70, 0x60
	s_cselect_b64 s[0:1], -1, 0
	v_writelane_b32 v253, s0, 11
	s_sext_i32_i16 s5, s4
	s_mov_b32 s11, s94
	v_writelane_b32 v253, s1, 12
	s_and_b64 s[0:1], s[0:1], exec
	s_cselect_b32 s18, 0, s8
	s_cselect_b32 s24, 0, 0xc0
	s_bfe_u32 s0, s18, 0x3001c
	s_add_i32 s0, s18, s0
	s_sext_i32_i16 s1, s0
	s_and_b32 s0, s0, 0xfff8
	s_ashr_i32 s19, s18, 31
	s_ashr_i32 s1, s1, 3
	s_sub_i32 s0, s18, s0
	s_cmp_lt_i32 s5, 0
	s_cselect_b32 s8, 49, 48
	s_mul_i32 s4, s8, s4
	s_add_i32 s4, s4, s3
	s_sext_i32_i16 s3, s4
	s_mulk_i32 s3, 0x2aab
	s_lshr_b32 s8, s3, 31
	s_ashr_i32 s3, s3, 19
	s_add_i32 s3, s3, s8
	s_mul_i32 s8, s3, 48
	s_sub_i32 s4, s4, s8
	s_bfe_i32 s8, s4, 0x80000
	s_bfe_u32 s8, s8, 0x3000c
	s_add_i32 s8, s4, s8
	s_bfe_i32 s9, s8, 0x80000
	s_and_b32 s8, s8, 0xf8
	s_sub_i32 s4, s4, s8
	s_lshl_b32 s3, s3, 3
	s_sext_i32_i16 s9, s9
	s_sext_i32_i8 s4, s4
	s_add_i32 s72, s3, s4
	s_ashr_i32 s3, s9, 3
	v_writelane_b32 v253, s3, 13
	s_ashr_i32 s15, s14, 31
	s_sext_i32_i16 s5, s0
	v_writelane_b32 v253, s14, 14
	s_lshl_b32 s3, s7, 3
	s_cmp_lt_i32 s5, 0
	v_writelane_b32 v253, s15, 15
	v_writelane_b32 v253, s3, 16
	s_cselect_b32 s3, 25, 24
	s_mul_i32 s0, s3, s0
	s_add_i32 s0, s0, s1
	s_abs_i32 s5, s58
	s_sext_i32_i16 s1, s0
	v_cvt_f32_u32_e32 v1, s5
	s_mulk_i32 s1, 0x2aab
	s_lshr_b32 s3, s1, 31
	s_ashr_i32 s1, s1, 18
	s_add_i32 s1, s1, s3
	s_lshl_b32 s3, s1, 3
	s_mul_i32 s1, s1, 24
	v_rcp_iflag_f32_e32 v1, v1
	s_sub_i32 s0, s0, s1
	s_bfe_i32 s1, s0, 0x80000
	s_bfe_u32 s1, s1, 0x3000c
	s_add_i32 s1, s0, s1
	v_mul_f32_e32 v1, 0x4f7ffffe, v1
	s_bfe_i32 s4, s1, 0x80000
	s_and_b32 s1, s1, 0xf8
	v_cvt_u32_f32_e32 v1, v1
	s_sub_i32 s0, s0, s1
	s_sext_i32_i8 s0, s0
	s_sext_i32_i16 s4, s4
	s_add_i32 s0, s3, s0
	v_writelane_b32 v253, s0, 17
	s_ashr_i32 s0, s4, 3
	s_sub_i32 s3, 0, s5
	v_readfirstlane_b32 s4, v1
	s_mul_i32 s3, s3, s4
	s_mul_hi_u32 s3, s4, s3
	s_abs_i32 s1, s2
	s_add_i32 s3, s4, s3
	s_mul_hi_u32 s4, s1, s3
	s_mul_i32 s4, s4, s5
	s_sub_i32 s1, s1, s4
	v_writelane_b32 v253, s0, 18
	s_ashr_i32 s0, s2, 31
	s_sub_i32 s4, s1, s5
	s_cmp_ge_u32 s1, s5
	s_cselect_b32 s1, s4, s1
	s_sub_i32 s4, s1, s5
	s_cmp_ge_u32 s1, s5
	s_cselect_b32 s1, s4, s1
	s_xor_b32 s1, s1, s0
	s_sub_i32 s33, s1, s0
	s_ashr_i32 s4, s33, 31
	s_cmpk_lt_i32 s33, 0x480
	s_cselect_b64 s[0:1], -1, 0
	v_writelane_b32 v253, s0, 19
	v_and_b32_e32 v4, 0x3fffffff, v0
	v_writelane_b32 v254, s10, 0
	v_writelane_b32 v253, s1, 20
	s_mul_hi_i32 s0, s33, 0x38e38e39
	s_lshr_b32 s1, s0, 31
	s_lshr_b32 s0, s0, 8
	s_add_i32 s0, s0, s1
	s_mulk_i32 s0, 0x480
	s_sub_i32 s0, s33, s0
	s_sext_i32_i16 s1, s0
	s_bfe_u32 s1, s1, 0x3001c
	s_add_i32 s1, s0, s1
	s_sext_i32_i16 s7, s1
	s_and_b32 s1, s1, 0xfff8
	s_sub_i32 s0, s0, s1
	s_ashr_i32 s7, s7, 3
	s_sext_i32_i16 s1, s0
	s_cmp_lt_i32 s1, 0
	s_movk_i32 s1, 0x91
	s_cselect_b32 s1, s1, 0x90
	s_mul_i32 s0, s0, s1
	s_add_i32 s0, s0, s7
	s_sext_i32_i16 s1, s0
	s_mulk_i32 s1, 0xe39
	s_lshr_b32 s7, s1, 31
	s_ashr_i32 s1, s1, 19
	s_add_i32 s1, s1, s7
	s_lshl_b32 s7, s1, 3
	s_mulk_i32 s1, 0x90
	s_sub_i32 s0, s0, s1
	s_sext_i32_i16 s1, s0
	s_bfe_u32 s1, s1, 0x3001c
	s_add_i32 s1, s0, s1
	s_sext_i32_i16 s8, s1
	s_and_b32 s1, s1, 0xfff8
	s_sub_i32 s0, s0, s1
	s_sext_i32_i16 s0, s0
	s_add_i32 s0, s7, s0
	v_writelane_b32 v253, s0, 21
	s_ashr_i32 s0, s8, 3
	v_writelane_b32 v253, s0, 22
	s_cmpk_lt_i32 s33, 0x6c
	v_writelane_b32 v254, s11, 1
	v_writelane_b32 v253, s1, 23
	s_cselect_b64 s[0:1], -1, 0
	v_writelane_b32 v253, s0, 24
	s_mov_b32 s75, s94
	v_mov_b64_e32 v[2:3], s[80:81]
	v_writelane_b32 v253, s1, 25
	s_mul_hi_i32 s0, s33, 0x4bda12f7
	s_lshr_b32 s1, s0, 31
	s_lshr_b32 s0, s0, 5
; #define LAS __attribute__((address_space(3)))
;     DI bool next(int i, Unit& u) const {
;         const long L = (long)base + (long)i * G + c; if (L >= nwg) return false;
;         const int z = (int)(L / per); int wgid = (int)(L % per);
;         if (per >= 64) { const int q = per / NXCD, r = per % NXCD, xcd = wgid % NXCD, off = wgid / NXCD; wgid = (xcd < r ? xcd * (q + 1) : r * (q + 1) + (xcd - r) * q) + off; }
;         const int nig = WGM * nN, gid = wgid / nig, fm = gid * WGM, gsz = (nM - fm) < WGM ? (nM - fm) : WGM;
;         u.pm = fm + ((wgid % nig) % gsz); u.pn = (wgid % nig) / gsz; u.z = z; return true;
; __global__ void __launch_bounds__(512, 2) mega(Params P) {
;     extern __shared__ __attribute__((aligned(16))) unsigned char smem_raw[];
;     LAS unsigned char* lds = (LAS unsigned char*)smem_raw;
;     cg::grid_group grid = cg::this_grid();
;     const int G = gridDim.x, blk = blockIdx.x;
;     Sched S;
;     ...
;     for (int layer = 0; layer < DEPTH; ++layer) {
	s_add_i32 s0, s0, s1
	s_mulk_i32 s0, 0x6c
	s_sub_i32 s0, s33, s0
	s_bfe_i32 s1, s0, 0x80000
	s_bfe_u32 s1, s1, 0x3000c
	s_add_i32 s1, s0, s1
	s_bfe_i32 s7, s1, 0x80000
	s_sext_i32_i16 s7, s7
	s_lshr_b32 s7, s7, 3
	s_and_b32 s1, s1, 0xfff8
	v_writelane_b32 v253, s7, 26
	s_sub_i32 s7, s0, s1
	s_bfe_i32 s0, s7, 0x80000
	s_sext_i32_i16 s0, s0
	s_cmp_gt_i32 s0, 3
	s_cselect_b64 s[0:1], -1, 0
	v_writelane_b32 v253, s0, 27
	s_mov_b32 s25, s94
	v_and_b32_e32 v232, 0x3ff, v0
	v_writelane_b32 v253, s1, 28
	s_mul_i32 s0, s7, 13
	s_add_i32 s0, s0, 4
	v_writelane_b32 v253, s0, 29
	s_mul_hi_u32 s0, s3, 0x6c
	s_mul_i32 s0, s0, s5
	s_sub_i32 s0, 0x6c, s0
	s_sub_i32 s1, s0, s5
	s_cmp_ge_u32 s0, s5
	s_cselect_b32 s0, s1, s0
	s_sub_i32 s1, s0, s5
	s_cmp_ge_u32 s0, s5
	s_cselect_b32 s0, s1, s0
	s_sub_i32 s0, s2, s0
	s_ashr_i32 s1, s0, 31
	s_abs_i32 s0, s0
	s_mul_hi_u32 s2, s0, s3
	s_mul_i32 s2, s2, s5
	s_sub_i32 s0, s0, s2
	s_sub_i32 s2, s0, s5
	s_cmp_ge_u32 s0, s5
	s_cselect_b32 s0, s2, s0
	s_sub_i32 s2, s0, s5
	s_cmp_ge_u32 s0, s5
	s_cselect_b32 s0, s2, s0
	s_xor_b32 s0, s0, s1
	s_sub_i32 s1, s0, s1
	s_ashr_i32 s0, s1, 31
	s_cmp_lt_i32 s1, 48
	v_writelane_b32 v253, s0, 30
	s_cselect_b64 s[8:9], -1, 0
	s_lshr_b32 s0, s1, 31
	v_writelane_b32 v253, s8, 31
	s_add_i32 s0, s1, s0
	s_mov_b32 s13, s94
	v_writelane_b32 v253, s9, 32
	s_ashr_i32 s8, s0, 1
	s_and_b32 s0, s0, -2
	s_sub_i32 s2, s1, s0
	v_writelane_b32 v253, s1, 33
	s_mov_b32 s0, s2
	v_writelane_b32 v253, s0, 34
	s_ashr_i32 s9, s8, 31
	v_mbcnt_lo_u32_b32 v5, -1, 0
	v_writelane_b32 v253, s1, 35
	s_bfe_i64 s[0:1], s[2:3], 0x80000
	s_mul_hi_i32 s1, s0, 0x60000
	v_writelane_b32 v253, s1, 36
	s_mul_i32 s0, s0, 0x60000
	v_writelane_b32 v253, s0, 37
	s_abs_i32 s0, s6
	s_mov_b32 s2, s8
	s_mul_hi_u32 s1, s0, s3
	v_writelane_b32 v253, s2, 38
	s_mul_i32 s1, s1, s5
	s_sub_i32 s0, s0, s1
	v_writelane_b32 v253, s3, 39
	s_lshl_b64 s[2:3], s[8:9], 18
	v_writelane_b32 v253, s2, 40
	s_ashr_i32 s1, s6, 31
	v_mov_b32_e32 v189, 0
	v_writelane_b32 v253, s3, 41
	s_sub_i32 s2, s0, s5
	s_cmp_ge_u32 s0, s5
	s_cselect_b32 s0, s2, s0
	s_sub_i32 s2, s0, s5
	s_cmp_ge_u32 s0, s5
	s_cselect_b32 s0, s2, s0
	s_xor_b32 s0, s0, s1
	s_sub_i32 s0, s0, s1
	s_cmpk_lt_i32 s0, 0xc0
	s_cselect_b64 s[2:3], -1, 0
	v_writelane_b32 v253, s2, 42
	s_lshl_b32 s0, s0, 9
	s_cmpk_lt_i32 s33, 0x100
	v_writelane_b32 v253, s3, 43
	v_writelane_b32 v253, s0, 44
	s_cselect_b64 s[0:1], -1, 0
	v_writelane_b32 v253, s0, 45
	v_mov_b32_e32 v251, 0x1e000000
	v_mbcnt_hi_u32_b32 v233, -1, v5
	v_writelane_b32 v253, s1, 46
	s_lshr_b32 s0, s4, 24
	s_add_i32 s0, s33, s0
	s_and_b32 s0, s0, 0xff00
	s_sub_i32 s0, s33, s0
	s_sext_i32_i16 s1, s0
	s_bfe_u32 s1, s1, 0x3001c
	s_add_i32 s1, s0, s1
	s_and_b32 s2, s1, 0xfff8
	s_sub_i32 s2, s0, s2
	s_sext_i32_i16 s0, s1
	s_lshr_b32 s0, s0, 3
	v_writelane_b32 v253, s0, 47
	s_sext_i32_i16 s0, s2
	s_cmp_gt_i32 s0, -1
	s_cselect_b64 s[0:1], -1, 0
	v_writelane_b32 v253, s0, 48
	v_mov_b32_e32 v252, 0xfffffe80
	v_mov_b32_e32 v250, 0x700
	v_writelane_b32 v253, s1, 49
	s_lshl_b32 s0, s2, 5
	s_cmpk_lt_i32 s33, 0x60
	v_writelane_b32 v253, s0, 50
	s_cselect_b64 s[0:1], -1, 0
	v_writelane_b32 v253, s0, 51
	v_mov_b32_e32 v238, 1
	v_mov_b64_e32 v[190:191], 0x480
	v_writelane_b32 v253, s1, 52
	s_lshr_b32 s0, s4, 30
	s_add_i32 s3, s33, s0
	s_and_b32 s0, s3, 0xfffc
	s_sub_i32 s0, s33, s0
	s_bfe_u32 s1, s0, 0x10007
	s_add_i32 s5, s0, s1
	s_and_b32 s1, s5, 0xfffe
	s_sub_i32 s0, s0, s1
	s_sext_i32_i8 s1, s0
	v_writelane_b32 v253, s1, 53
	s_bfe_i64 s[0:1], s[0:1], 0x80000
	s_mul_hi_i32 s1, s0, 0x60000
	v_writelane_b32 v253, s1, 54
	s_mul_i32 s0, s0, 0x60000
	v_writelane_b32 v253, s0, 55
	s_bfe_i32 s0, s5, 0x80000
	s_sext_i32_i16 s0, s0
	s_ashr_i32 s6, s3, 2
	s_ashr_i32 s0, s0, 1
	s_cmpk_lt_i32 s33, 0x400
	v_writelane_b32 v253, s0, 56
	s_cselect_b64 s[0:1], -1, 0
; #define LAS __attribute__((address_space(3)))
; DI int opq0() { int z = 0; asm volatile("" : "+s"(z)); return z; }
; __global__ void __launch_bounds__(512, 2) mega(Params P) {
;     extern __shared__ __attribute__((aligned(16))) unsigned char smem_raw[];
;     LAS unsigned char* lds = (LAS unsigned char*)smem_raw;
;     cg::grid_group grid = cg::this_grid();
;     const int G = gridDim.x, blk = blockIdx.x;
;     Sched S;
;     ...
;     for (int layer = 0; layer < DEPTH; ++layer) {
;         { TID_VARS; if (layer == 0 && tid == 0) *(volatile LAS unsigned*)(lds + 131072) = 0u; if (layer == 0 && blk == 0) { unsigned* bw = (unsigned*)(P.ws + opq0() + WS_BAR); for (int i = tid; i < 4096; i += 512) bw[i] = 0u; } phase_prep(P, layer, blk * 512 + tid, G * 512); }
	v_writelane_b32 v253, s0, 57
	v_mov_b64_e32 v[192:193], 0x47f
	v_mov_b64_e32 v[194:195], 0x6c
	v_writelane_b32 v253, s1, 58
	s_lshr_b32 s0, s4, 22
	s_add_i32 s0, s33, s0
	s_and_b32 s0, s0, 0xfc00
	s_sub_i32 s0, s33, s0
	s_sext_i32_i16 s1, s0
	s_bfe_u32 s1, s1, 0x3001c
	s_add_i32 s1, s0, s1
	s_and_b32 s3, s1, 0xfff8
	s_sext_i32_i16 s1, s1
	s_sub_i32 s0, s0, s3
	s_lshr_b32 s1, s1, 3
	v_writelane_b32 v253, s1, 59
	s_sext_i32_i16 s1, s0
	s_cmp_gt_i32 s1, -1
	s_mul_i32 s1, s7, 14
	v_writelane_b32 v254, s1, 2
	s_mul_i32 s1, s2, 33
	v_writelane_b32 v254, s1, 3
	s_cselect_b64 s[2:3], -1, 0
	v_writelane_b32 v254, s2, 4
	s_lshl_b32 s1, s0, 7
	s_mulk_i32 s0, 0x81
	v_writelane_b32 v254, s3, 5
	v_writelane_b32 v254, s1, 6
	v_writelane_b32 v254, s0, 7
	s_add_u32 s0, s22, 0x1e000000
	v_writelane_b32 v254, s0, 8
	s_addc_u32 s0, s23, 0
	v_writelane_b32 v254, s0, 9
	s_lshl_b32 s0, s70, 12
	v_writelane_b32 v254, s0, 10
	s_lshl_b32 s0, s58, 12
	v_writelane_b32 v254, s0, 11
	s_add_u32 s0, s22, 4
	v_writelane_b32 v254, s0, 12
	s_addc_u32 s0, s23, 0
	v_writelane_b32 v254, s0, 13
	s_mul_hi_i32 s0, s6, 0xc0000
	v_writelane_b32 v254, s0, 14
	v_writelane_b32 v254, s6, 15
	s_mul_i32 s0, s6, 0xc0000
	v_writelane_b32 v254, s0, 16
	s_lshl_b32 s0, s70, 11
	s_ashr_i32 s35, s34, 31
	v_writelane_b32 v254, s0, 17
	s_lshl_b32 s0, s58, 11
	s_ashr_i32 s85, s84, 31
	v_writelane_b32 v254, s0, 18
	s_lshl_b64 s[0:1], s[34:35], 12
	s_ashr_i32 s17, s16, 31
	s_lshl_b64 s[90:91], s[84:85], 3
	v_writelane_b32 v254, s0, 19
	v_cmp_eq_u32_e64 s[6:7], 0, v4
	v_writelane_b32 v253, s18, 60
	v_writelane_b32 v254, s1, 20
	s_add_u32 s0, s22, 0x1a000400
	v_writelane_b32 v254, s0, 21
	s_addc_u32 s0, s23, 0
	v_writelane_b32 v254, s0, 22
	v_writelane_b32 v254, s16, 23
	s_add_i32 s0, s16, 0xfffff800
	s_lshl_b64 s[62:63], s[34:35], 11
	v_writelane_b32 v254, s17, 24
	v_writelane_b32 v254, s0, 25
	s_add_u32 s0, s22, 0xaa00100
	v_writelane_b32 v254, s0, 26
	s_addc_u32 s0, s23, 0
	v_writelane_b32 v254, s0, 27
	s_add_u32 s0, s22, 0xb600000
	v_writelane_b32 v254, s0, 28
	v_writelane_b32 v254, s20, 29
	s_addc_u32 s0, s23, 0
	v_mov_b64_e32 v[0:1], s[18:19]
	v_writelane_b32 v254, s21, 30
	v_writelane_b32 v254, s22, 31
	v_writelane_b32 v254, s23, 32
	v_writelane_b32 v254, s0, 33
	s_add_i32 s0, 0, 0x20000
	v_writelane_b32 v254, s0, 34
	v_writelane_b32 v254, s6, 35
	v_writelane_b32 v253, s19, 61
	v_writelane_b32 v253, s12, 62
	v_writelane_b32 v254, s7, 36
	v_cmp_gt_i64_e64 s[6:7], s[74:75], v[2:3]
	v_writelane_b32 v253, s13, 63
	v_mov_b64_e32 v[196:197], 0x6b
	v_writelane_b32 v254, s6, 37
	v_mov_b64_e32 v[198:199], 0x100
	v_mov_b64_e32 v[200:201], 0xff
	v_writelane_b32 v254, s7, 38
	v_writelane_b32 v254, s24, 39
	v_mov_b64_e32 v[202:203], 0x60
	v_mov_b64_e32 v[204:205], 0x5f
	v_writelane_b32 v254, s25, 40
	v_cmp_gt_i64_e64 s[6:7], s[24:25], v[0:1]
	v_mov_b64_e32 v[206:207], 0x400
	v_mov_b64_e32 v[208:209], 0x3ff
	v_writelane_b32 v254, s6, 41
	s_movk_i32 s95, 0x60
	s_movk_i32 s18, 0x300
	v_writelane_b32 v254, s7, 42
	v_writelane_b32 v254, s62, 43
	s_movk_i32 s73, 0xc00
	s_mov_b32 s61, 0xc000
	v_writelane_b32 v254, s63, 44
	v_writelane_b32 v254, s66, 45
	s_movk_i32 s92, 0x600
	s_movk_i32 s93, 0x1800
	v_writelane_b32 v254, s67, 46
	v_writelane_b32 v254, s70, 47
	v_writelane_b32 v254, s74, 48
	s_mov_b32 s85, 0x3c800000
	s_movk_i32 s5, 0x2000
	v_writelane_b32 v254, s75, 49
	v_writelane_b32 v254, s80, 50
	s_movk_i32 s1, 0x4000
	s_movk_i32 s88, 0x8ff
	v_writelane_b32 v254, s81, 51
	v_writelane_b32 v254, s34, 52
	s_mov_b32 s60, 0x39800000
	s_movk_i32 s3, 0x801
	v_writelane_b32 v254, s35, 53
	v_writelane_b32 v254, s71, 54
	v_writelane_b32 v254, s72, 55
	v_writelane_b32 v254, s90, 56
	s_mov_b64 s[38:39], -1
	s_mov_b64 s[56:57], 0x80
	s_mov_b32 s78, 0x3e16c740
	s_mov_b32 s10, 0
	s_brev_b32 s36, 1
	v_writelane_b32 v254, s91, 57
	s_branch .LBB0_2

; #define LAS __attribute__((address_space(3)))
; DI int opq0() { int z = 0; asm volatile("" : "+s"(z)); return z; }
; DI int tid_opq() { int t = threadIdx.x; asm volatile("" : "+v"(t)); return t; }
; DI unsigned xb_ld(unsigned* p)              { return __hip_atomic_load(p, __ATOMIC_RELAXED, __HIP_MEMORY_SCOPE_AGENT); }
; DI unsigned xb_add(unsigned* p, unsigned v) { return __hip_atomic_fetch_add(p, v, __ATOMIC_RELAXED, __HIP_MEMORY_SCOPE_AGENT); }
; DI void flat_barrier(unsigned char* wsb, LAS unsigned char* ldsb) {
;     asm volatile("s_waitcnt vmcnt(0)" ::: "memory");
;     __syncthreads();
;     if (tid_opq() == 0) {
;         unsigned* cnt = (unsigned*)(wsb + opq0() + WS_BAR) + 64;
;         const unsigned G = gridDim.x;
;         __builtin_amdgcn_fence(__ATOMIC_RELEASE, "agent");
;         asm volatile("s_waitcnt vmcnt(0)" ::: "memory");
;         volatile LAS unsigned* st = (volatile LAS unsigned*)(ldsb + 131072);
;         const unsigned k = st[0] + 1u; st[0] = k;
;         (void)xb_add(cnt, 1u);
;         const unsigned target = k * G;
;         unsigned sp = 0u;
;         while (xb_ld(cnt) < target) { __builtin_amdgcn_s_sleep(1); if (++sp > (1u << 24)) break; }
;         __builtin_amdgcn_fence(__ATOMIC_ACQUIRE, "agent");
;         asm volatile("s_waitcnt vmcnt(0)" ::: "memory");
;     }
;     __syncthreads();
; }
.LBB0_737:
	s_waitcnt vmcnt(0)
	v_mov_b32_e32 v0, v232
	s_waitcnt vmcnt(0)
	s_barrier
	s_nop 0
	v_cmp_gt_u32_e32 vcc, 16, v0
	s_and_saveexec_b64 s[6:7], vcc
	s_cbranch_execz .LBB0_754
	buffer_wbl2 sc1
	s_waitcnt vmcnt(0)
	v_readlane_b32 s0, v254, 34
	v_readlane_b32 s8, v254, 31
	v_readlane_b32 s9, v254, 32
	v_readlane_b32 s2, v255, 9
	s_nop 3
	v_mov_b32_e32 v0, s0
	ds_read_b32 v1, v0
	s_add_u32 s8, s8, s94
	s_addc_u32 s9, s9, 0
	s_add_u32 s8, s8, 0x1e002000
	s_addc_u32 s9, s9, 0
	s_and_b32 s2, s2, 15
	s_lshl_b32 s2, s2, 7
	s_waitcnt lgkmcnt(0)
	v_add_u32_e32 v1, 1, v1
	ds_write_b32 v0, v1
	s_waitcnt lgkmcnt(0)
	v_readfirstlane_b32 s0, v1
	s_mov_b64 vcc, exec
	s_mov_b64 exec, 1
	v_mov_b32_e32 v0, s2
	v_mov_b32_e32 v1, 1
	global_atomic_add v0, v1, s[8:9]
	s_mov_b64 exec, vcc
	s_add_u32 s2, s58, 15
	v_sub_u32_e32 v0, s2, v232
	v_lshrrev_b32_e32 v0, 4, v0
	v_mul_lo_u32 v0, v0, s0
	s_mov_b32 s2, 0x4000
.Lnb_poll0:
	v_lshlrev_b32_e32 v1, 7, v232
	global_load_dword v1, v1, s[8:9] sc1
	s_waitcnt vmcnt(0)
	v_cmp_lt_u32_e32 vcc, v1, v0
	s_cbranch_vccz .Lnb_acq0
	s_sleep 1
	s_sub_u32 s2, s2, 1
	s_cmp_lg_u32 s2, 0
	s_cbranch_scc1 .Lnb_poll0
.Lnb_acq0:
	buffer_inv sc1
	s_waitcnt vmcnt(0)
.LBB0_754:
	s_or_b64 exec, exec, s[6:7]
	v_readlane_b32 s8, v253, 24
	v_readlane_b32 s9, v253, 25
	s_mov_b32 s6, s94
	v_mov_b32_e32 v8, v232
	v_cndmask_b32_e64 v0, 0, 1, s[8:9]
	s_barrier
	v_cmp_ne_u32_e64 s[10:11], 1, v0
	s_andn2_b64 vcc, exec, s[8:9]
	v_readfirstlane_b32 s2, v8
	s_cbranch_vccnz .LBB0_758
	v_readlane_b32 s8, v253, 27
	v_readlane_b32 s9, v253, 28
	s_andn2_b64 vcc, exec, s[8:9]
	v_readlane_b32 s7, v254, 2
	s_cbranch_vccnz .LBB0_757
	v_readlane_b32 s7, v253, 29

; DI int opq0() { int z = 0; asm volatile("" : "+s"(z)); return z; }
; DI float2 cpowe(const S5c& c, float e) { const float mg = __expf(e * c.a); float s, co; sincos_rev(e * c.b * 0.15915494309189535f, s, co); return make_float2(mg * co, mg * s); }
; DI void phase_s5_scan(const Params& P, int layer, int t) {
;     if (t >= CSEQ * S5G * 2 * 64 * 8) return;
;     const int n = (t & 7) | (((t >> 6) & 7) << 3), j = (t >> 3) & 7, rest = t >> 9, d = rest & 1, g = (rest >> 1) % S5G, bl = (rest >> 1) / S5G;
;     const int z = opq0(); const S5c c = s5_load(P.in[I_LDT + z], P.in[I_LRE + z], P.in[I_LIM + z], layer, d, g, n);
;     const float2 lt = cpowe(c, (float)TCH), lt16 = cpowe(c, (float)(16 * TCH));
;     const float* s = (const float*)(P.ws + z + WS_S) + ((size_t)g * 512 + bl * 128) * 256 + d * 128 + n * 2;
;     bf16_t* u2 = (bf16_t*)(P.ws + z + WS_U2) + ((size_t)g * 512 + bl * 128) * U2LD + 512 + d * 128 + n * 2;
;     float2 sv[16], pf[16];
; #pragma unroll
;     for (int i = 0; i < 16; ++i) { const int k = 16 * j + i, cidx = d == 0 ? k : NCH - 1 - k; sv[i] = *(const float2*)(s + (size_t)cidx * 256); }
; DI void flat_barrier(unsigned char* wsb, LAS unsigned char* ldsb) {
;     ...
;         __builtin_amdgcn_fence(__ATOMIC_ACQUIRE, "agent");
;         asm volatile("s_waitcnt vmcnt(0)" ::: "memory");
;     }
;     __syncthreads();
.Lnb_acq1:
	buffer_inv sc1
	s_waitcnt vmcnt(0)
.LBB0_1034:
	s_or_b64 exec, exec, s[6:7]
	v_mov_b32_e32 v5, v232
	v_readlane_b32 s0, v253, 44
	v_readlane_b32 s6, v253, 42
	s_barrier
	v_readlane_b32 s7, v253, 43
	v_add_u32_e32 v0, s0, v5
	s_mov_b32 s0, 0x18000
	v_cndmask_b32_e64 v0, 2.0, v0, s[6:7]
	v_cmp_gt_i32_e32 vcc, s0, v0
	s_and_saveexec_b64 s[10:11], vcc
	s_cbranch_execz .LBB0_1036
	s_mov_b32 s6, s94
	v_and_b32_e32 v21, 7, v0
	v_lshrrev_b32_e32 v1, 3, v0
	s_ashr_i32 s7, s6, 31
	v_and_or_b32 v22, v1, 56, v21
	v_ashrrev_i32_e32 v1, 10, v0
	s_mov_b32 s0, 0x2aaaaaab
	s_lshl_b64 s[8:9], s[6:7], 3
	v_mul_hi_i32 v2, v1, s0
	s_add_u32 s8, s66, s8
	v_lshrrev_b32_e32 v3, 31, v2
	v_ashrrev_i32_e32 v2, 2, v2
	s_addc_u32 s9, s67, s9
	v_add_u32_e32 v3, v2, v3
	s_load_dwordx4 s[12:15], s[8:9], 0x28
	s_nop 0
	s_load_dwordx2 s[8:9], s[8:9], 0x38
	v_bfe_u32 v4, v0, 9, 1
	v_mul_lo_u32 v2, v3, 24
	v_readlane_b32 s0, v255, 1
	v_sub_u32_e32 v2, v1, v2
	v_bfe_u32 v14, v0, 3, 3
	v_or_b32_e32 v1, s0, v4
	v_mad_u32_u24 v6, v1, 24, v2
	v_ashrrev_i32_e32 v7, 31, v6
	s_waitcnt lgkmcnt(0)
	v_lshl_add_u64 v[8:9], v[6:7], 2, s[8:9]
	global_load_dword v10, v[8:9], off
	v_lshl_or_b32 v6, v6, 6, v22
	v_ashrrev_i32_e32 v7, 31, v6
	v_lshlrev_b64 v[6:7], 2, v[6:7]
	v_lshl_add_u64 v[8:9], s[12:13], 0, v[6:7]
	v_lshl_add_u64 v[6:7], s[14:15], 0, v[6:7]
	global_load_dword v11, v[8:9], off
	global_load_dword v23, v[6:7], off
	v_lshlrev_b32_e32 v50, 4, v14
	v_xor_b32_e32 v0, 0x7f, v50
	v_cmp_eq_u32_e32 vcc, 0, v4
	v_readlane_b32 s12, v254, 29
	v_or_b32_e32 v1, 1, v50
	v_xor_b32_e32 v6, 0x7e, v50
	v_cndmask_b32_e32 v20, v0, v50, vcc
	v_lshlrev_b32_e32 v0, 7, v3
	v_readlane_b32 s14, v254, 31
	v_ashrrev_i32_e32 v3, 31, v2
	v_cndmask_b32_e32 v19, v6, v1, vcc
	v_ashrrev_i32_e32 v1, 31, v0
	v_readlane_b32 s15, v254, 32
	s_add_u32 s6, s14, s6
	v_lshlrev_b64 v[2:3], 9, v[2:3]
	v_or_b32_e32 v7, 2, v50
	v_xor_b32_e32 v8, 0x7d, v50
	s_addc_u32 s7, s15, s7
	v_lshl_add_u64 v[0:1], v[2:3], 0, v[0:1]
	v_cndmask_b32_e32 v18, v8, v7, vcc
	v_mov_b64_e32 v[2:3], s[6:7]
	v_lshlrev_b64 v[6:7], 10, v[0:1]
	v_lshlrev_b32_e32 v188, 9, v4
	v_mad_u64_u32 v[2:3], s[8:9], v0, s92, v[2:3]
	v_lshl_add_u64 v[6:7], s[6:7], 0, v[6:7]
	v_mad_i32_i24 v3, v1, s92, v3
	v_lshl_add_u64 v[0:1], v[6:7], 0, v[188:189]
	v_lshlrev_b32_e32 v188, 3, v22
	v_lshl_add_u64 v[0:1], v[0:1], 0, v[188:189]
	v_lshlrev_b32_e32 v188, 8, v4
	s_mov_b64 s[6:7], 0x9e00000
	v_or_b32_e32 v13, 4, v50
	v_xor_b32_e32 v15, 0x7b, v50
	v_or_b32_e32 v24, 5, v50
	v_xor_b32_e32 v25, 0x7a, v50
	v_lshl_add_u64 v[0:1], v[0:1], 0, s[6:7]
	v_lshl_add_u64 v[2:3], v[2:3], 0, v[188:189]
	v_lshlrev_b32_e32 v188, 10, v20
	v_or_b32_e32 v9, 3, v50
	v_xor_b32_e32 v12, 0x7c, v50
	v_cndmask_b32_e32 v16, v15, v13, vcc
	v_cndmask_b32_e32 v15, v25, v24, vcc
	v_lshl_add_u64 v[24:25], v[0:1], 0, v[188:189]
	v_lshlrev_b32_e32 v188, 10, v19
	v_cndmask_b32_e32 v17, v12, v9, vcc
	v_lshl_add_u64 v[8:9], v[0:1], 0, v[188:189]
	v_lshlrev_b32_e32 v188, 10, v18
	v_lshl_add_u64 v[26:27], v[0:1], 0, v[188:189]
	v_lshlrev_b32_e32 v188, 10, v17
	v_lshl_add_u64 v[28:29], v[0:1], 0, v[188:189]
	v_lshlrev_b32_e32 v188, 10, v16
	v_lshl_add_u64 v[12:13], v[0:1], 0, v[188:189]
	v_lshlrev_b32_e32 v188, 10, v15
	v_xor_b32_e32 v34, 0x78, v50
	v_lshl_add_u64 v[30:31], v[0:1], 0, v[188:189]
	v_xor_b32_e32 v36, 0x77, v50
	v_xor_b32_e32 v38, 0x76, v50
	v_xor_b32_e32 v40, 0x75, v50
	v_xor_b32_e32 v42, 0x74, v50
	v_xor_b32_e32 v44, 0x73, v50
	v_xor_b32_e32 v46, 0x72, v50
	v_xor_b32_e32 v48, 0x71, v50
	s_mov_b64 s[6:7], 0x8c00400
	v_readlane_b32 s13, v254, 30
	s_waitcnt vmcnt(2)
	v_mul_f32_e32 v4, 0x3fb8aa3b, v10
	v_exp_f32_e32 v4, v4
	s_waitcnt vmcnt(1)
	v_mul_f32_e32 v6, v11, v4
	s_waitcnt vmcnt(0)
	v_mul_f32_e32 v4, v23, v4
	v_mul_f32_e32 v10, 0x42000000, v4
	v_mul_f32_e32 v7, 0x42000000, v6
	v_mul_f32_e32 v6, 0x44000000, v6
	v_mul_f32_e32 v11, 0x44000000, v4
	v_mul_f32_e32 v4, 0.15915494, v10
	v_mul_f32_e32 v6, 0x3fb8aa3b, v6
	v_mul_f32_e32 v23, 0.15915494, v11
	v_floor_f32_e32 v32, v4
	v_exp_f32_e32 v4, v6
	v_floor_f32_e32 v6, v23
	v_fma_f32 v23, v10, 0.15915494, -v32
	v_fma_f32 v51, v11, 0.15915494, -v6
	v_sin_f32_e32 v10, v23
	v_cos_f32_e32 v11, v23
	v_or_b32_e32 v23, 6, v50
	v_xor_b32_e32 v32, 0x79, v50
	v_cndmask_b32_e32 v60, v32, v23, vcc
	global_load_dwordx2 v[32:33], v[8:9], off
	s_nop 0
	global_load_dwordx2 v[8:9], v[28:29], off
	s_nop 0
	global_load_dwordx2 v[26:27], v[26:27], off
	s_nop 0
	global_load_dwordx2 v[24:25], v[24:25], off
	v_or_b32_e32 v23, 7, v50
	v_lshlrev_b32_e32 v188, 10, v60
	v_cndmask_b32_e32 v62, v34, v23, vcc
	v_lshl_add_u64 v[28:29], v[0:1], 0, v[188:189]
	v_lshlrev_b32_e32 v188, 10, v62
	v_lshl_add_u64 v[34:35], v[0:1], 0, v[188:189]
	global_load_dwordx2 v[30:31], v[30:31], off
	s_nop 0
	global_load_dwordx2 v[34:35], v[34:35], off
	s_nop 0
	global_load_dwordx2 v[28:29], v[28:29], off
	s_nop 0
	global_load_dwordx2 v[12:13], v[12:13], off
	v_or_b32_e32 v23, 8, v50
	v_cndmask_b32_e32 v64, v36, v23, vcc
	v_or_b32_e32 v23, 9, v50
	v_lshlrev_b32_e32 v188, 10, v64
	v_cndmask_b32_e32 v66, v38, v23, vcc
	v_or_b32_e32 v23, 10, v50
	v_lshl_add_u64 v[36:37], v[0:1], 0, v[188:189]
	v_lshlrev_b32_e32 v188, 10, v66
	v_cndmask_b32_e32 v68, v40, v23, vcc
	v_or_b32_e32 v23, 11, v50
	v_lshl_add_u64 v[38:39], v[0:1], 0, v[188:189]
	v_lshlrev_b32_e32 v188, 10, v68
	v_cndmask_b32_e32 v80, v42, v23, vcc
	v_or_b32_e32 v23, 12, v50
	v_lshl_add_u64 v[40:41], v[0:1], 0, v[188:189]
	v_lshlrev_b32_e32 v188, 10, v80
	v_cndmask_b32_e32 v81, v44, v23, vcc
	v_or_b32_e32 v23, 13, v50
	v_lshl_add_u64 v[42:43], v[0:1], 0, v[188:189]
	v_lshlrev_b32_e32 v188, 10, v81
	v_cndmask_b32_e32 v82, v46, v23, vcc
; DI unsigned pk2(float lo, float hi) { const f32x2_t v = {lo, hi}; return __builtin_bit_cast(unsigned, __builtin_convertvector(v, bf16x2_t)); }
; DI float2 cmul(float2 x, float2 y) { return make_float2(x.x * y.x - x.y * y.y, x.x * y.y + x.y * y.x); }
; DI void phase_s5_scan(const Params& P, int layer, int t) {
;     ...
;     float2 H = make_float2(0.f, 0.f);
; #pragma unroll
;     for (int i = 0; i < 16; ++i) { pf[i] = H; const float2 nh = cmul(lt, H); H = make_float2(nh.x + sv[i].x, nh.y + sv[i].y); }
;     ...
;     for (int i = 0; i < 16; ++i) {
;         const int k = 16 * j + i, cidx = d == 0 ? k : NCH - 1 - k;
;         *(unsigned*)(u2 + (size_t)cidx * U2LD) = pk2(W.x + pf[i].x, W.y + pf[i].y);
	v_or_b32_e32 v23, 14, v50
	v_lshl_add_u64 v[44:45], v[0:1], 0, v[188:189]
	v_lshlrev_b32_e32 v188, 10, v82
	v_cndmask_b32_e32 v83, v48, v23, vcc
	v_or_b32_e32 v23, 15, v50
	v_xor_b32_e32 v50, 0x70, v50
	v_lshl_add_u64 v[46:47], v[0:1], 0, v[188:189]
	v_lshlrev_b32_e32 v188, 10, v83
	v_cndmask_b32_e32 v84, v50, v23, vcc
	v_lshl_add_u64 v[48:49], v[0:1], 0, v[188:189]
	v_lshlrev_b32_e32 v188, 10, v84
	v_lshl_add_u64 v[0:1], v[0:1], 0, v[188:189]
	global_load_dwordx2 v[52:53], v[0:1], off
	s_nop 0
	global_load_dwordx2 v[44:45], v[44:45], off
	s_nop 0
	global_load_dwordx2 v[46:47], v[46:47], off
	s_nop 0
	global_load_dwordx2 v[48:49], v[48:49], off
	v_lshlrev_b32_e32 v188, 2, v22
	global_load_dwordx2 v[22:23], v[42:43], off
	s_nop 0
	global_load_dwordx2 v[38:39], v[38:39], off
	s_nop 0
	global_load_dwordx2 v[40:41], v[40:41], off
	s_nop 0
	global_load_dwordx2 v[36:37], v[36:37], off
	v_mul_f32_e32 v7, 0x3fb8aa3b, v7
	v_exp_f32_e32 v50, v7
	v_cos_f32_e32 v6, v51
	v_sin_f32_e32 v7, v51
	v_lshl_add_u64 v[2:3], v[2:3], 0, v[188:189]
	v_pk_mul_f32 v[0:1], v[50:51], v[10:11] op_sel_hi:[0,1]
	v_mul_f32_e32 v10, 0, v0
	v_pk_fma_f32 v[50:51], v[0:1], 0, v[10:11] op_sel:[1,0,0] op_sel_hi:[0,1,0] neg_lo:[0,0,1] neg_hi:[0,0,1]
	v_pk_fma_f32 v[10:11], v[0:1], 0, v[10:11] op_sel_hi:[1,1,0]
	v_pk_mul_f32 v[6:7], v[4:5], v[6:7] op_sel_hi:[0,1]
	v_and_or_b32 v10, v233, 64, v21
	v_mov_b32_e32 v51, v11
	v_lshlrev_b32_e32 v77, 2, v10
	v_mul_f32_e32 v4, 0, v6
	v_mul_f32_e32 v43, 0, v7
	v_sub_f32_e32 v42, v4, v43
	v_mul_u32_u24_e32 v4, 0x300, v20
	v_lshlrev_b32_e32 v188, 1, v4
	v_lshl_add_u64 v[2:3], v[2:3], 0, s[6:7]
	v_lshl_add_u64 v[20:21], v[2:3], 0, v[188:189]
	v_fmac_f32_e32 v43, 0, v6
	v_cmp_eq_u32_e32 vcc, 1, v14
	s_waitcnt vmcnt(12)
	v_pk_add_f32 v[10:11], v[24:25], v[50:51]
	s_nop 0
	v_pk_mul_f32 v[24:25], v[0:1], v[10:11] op_sel:[0,1]
	s_nop 0
	v_pk_fma_f32 v[50:51], v[0:1], v[10:11], v[24:25] op_sel:[1,0,0] op_sel_hi:[0,1,1] neg_lo:[0,0,1] neg_hi:[0,0,1]
	v_pk_fma_f32 v[24:25], v[0:1], v[10:11], v[24:25] op_sel:[1,0,0] op_sel_hi:[0,0,1]
	v_mov_b32_e32 v51, v25
	v_pk_add_f32 v[24:25], v[32:33], v[50:51]
	s_nop 0
	v_mul_f32_e32 v4, v0, v25
	v_pk_fma_f32 v[32:33], v[0:1], v[24:25], v[4:5] op_sel:[1,0,0] op_sel_hi:[0,1,0] neg_lo:[0,0,1] neg_hi:[0,0,1]
	v_mul_f32_e32 v4, v0, v24
	v_pk_fma_f32 v[50:51], v[0:1], v[24:25], v[4:5] op_sel_hi:[1,1,0]
	v_mul_u32_u24_e32 v4, 0x300, v19
	v_mov_b32_e32 v33, v51
	v_pk_add_f32 v[26:27], v[26:27], v[32:33]
	v_lshlrev_b32_e32 v188, 1, v4
	v_pk_mul_f32 v[32:33], v[0:1], v[26:27] op_sel:[0,1]
	v_mul_u32_u24_e32 v4, 0x300, v18
	v_pk_fma_f32 v[50:51], v[0:1], v[26:27], v[32:33] op_sel:[1,0,0] op_sel_hi:[0,1,1] neg_lo:[0,0,1] neg_hi:[0,0,1]
	v_pk_fma_f32 v[32:33], v[0:1], v[26:27], v[32:33] op_sel:[1,0,0] op_sel_hi:[0,0,1]
	v_mov_b32_e32 v51, v33
	v_pk_add_f32 v[8:9], v[8:9], v[50:51]
	v_lshl_add_u64 v[54:55], v[2:3], 0, v[188:189]
	v_lshlrev_b32_e32 v188, 1, v4
	v_mul_f32_e32 v4, v0, v9
	v_pk_fma_f32 v[32:33], v[0:1], v[8:9], v[4:5] op_sel:[1,0,0] op_sel_hi:[0,1,0] neg_lo:[0,0,1] neg_hi:[0,0,1]
	v_mul_f32_e32 v4, v0, v8
	v_pk_fma_f32 v[50:51], v[0:1], v[8:9], v[4:5] op_sel_hi:[1,1,0]
	v_mul_u32_u24_e32 v4, 0x300, v17
	v_mov_b32_e32 v33, v51
	s_waitcnt vmcnt(8)
	v_pk_add_f32 v[12:13], v[12:13], v[32:33]
	v_lshl_add_u64 v[18:19], v[2:3], 0, v[188:189]
	v_pk_mul_f32 v[32:33], v[0:1], v[12:13] op_sel:[0,1]
	v_lshlrev_b32_e32 v188, 1, v4
	v_pk_fma_f32 v[50:51], v[0:1], v[12:13], v[32:33] op_sel:[1,0,0] op_sel_hi:[0,1,1] neg_lo:[0,0,1] neg_hi:[0,0,1]
	v_pk_fma_f32 v[32:33], v[0:1], v[12:13], v[32:33] op_sel:[1,0,0] op_sel_hi:[0,0,1]
	v_mov_b32_e32 v51, v33
	v_mul_u32_u24_e32 v4, 0x300, v16
	v_pk_add_f32 v[30:31], v[30:31], v[50:51]
	v_lshl_add_u64 v[56:57], v[2:3], 0, v[188:189]
	v_lshlrev_b32_e32 v188, 1, v4
	v_mul_f32_e32 v4, v0, v31
	v_pk_fma_f32 v[32:33], v[0:1], v[30:31], v[4:5] op_sel:[1,0,0] op_sel_hi:[0,1,0] neg_lo:[0,0,1] neg_hi:[0,0,1]
	v_mul_f32_e32 v4, v0, v30
	v_pk_fma_f32 v[50:51], v[0:1], v[30:31], v[4:5] op_sel_hi:[1,1,0]
	v_mul_u32_u24_e32 v4, 0x300, v15
	v_mov_b32_e32 v33, v51
	v_pk_add_f32 v[28:29], v[28:29], v[32:33]
	v_lshl_add_u64 v[16:17], v[2:3], 0, v[188:189]
	v_pk_mul_f32 v[32:33], v[0:1], v[28:29] op_sel:[0,1]
	v_lshlrev_b32_e32 v188, 1, v4
	v_pk_fma_f32 v[50:51], v[0:1], v[28:29], v[32:33] op_sel:[1,0,0] op_sel_hi:[0,0,1]
	v_pk_fma_f32 v[32:33], v[0:1], v[28:29], v[32:33] op_sel:[1,0,0] op_sel_hi:[0,0,1] neg_lo:[0,0,1] neg_hi:[0,0,1]
	v_mov_b32_e32 v33, v51
	v_mul_u32_u24_e32 v4, 0x300, v60
	v_pk_add_f32 v[32:33], v[34:35], v[32:33]
	v_lshl_add_u64 v[58:59], v[2:3], 0, v[188:189]
	v_lshlrev_b32_e32 v188, 1, v4
	v_mul_f32_e32 v4, v0, v33
	v_pk_fma_f32 v[34:35], v[0:1], v[32:33], v[4:5] op_sel:[1,0,0] op_sel_hi:[0,1,0] neg_lo:[0,0,1] neg_hi:[0,0,1]
	v_mul_f32_e32 v4, v0, v32
	v_pk_fma_f32 v[50:51], v[0:1], v[32:33], v[4:5] op_sel_hi:[1,1,0]
	v_mul_u32_u24_e32 v4, 0x300, v62
	v_mov_b32_e32 v35, v51
	s_waitcnt vmcnt(0)
; DI float2 cmul(float2 x, float2 y) { return make_float2(x.x * y.x - x.y * y.y, x.x * y.y + x.y * y.x); }
; DI void phase_s5_scan(const Params& P, int layer, int t) {
;     ...
;     for (int i = 0; i < 16; ++i) { pf[i] = H; const float2 nh = cmul(lt, H); H = make_float2(nh.x + sv[i].x, nh.y + sv[i].y); }
;     const int lane = t & 63;
;     float2 C = make_float2(0.f, 0.f), mine = make_float2(0.f, 0.f);
; #pragma unroll
;     for (int m = 0; m < 8; ++m) {
;         if (m == j) mine = C;
;         const float ex = __shfl(H.x, (lane & 0x7) | (m << 3) | (lane & 0x38 & 0) , 64), ey = __shfl(H.y, (lane & 0x7) | (m << 3), 64);
;         const float2 nc = cmul(lt16, C); C = make_float2(nc.x + ex, nc.y + ey);
;     }
	v_pk_add_f32 v[34:35], v[36:37], v[34:35]
	v_lshl_add_u64 v[60:61], v[2:3], 0, v[188:189]
	v_pk_mul_f32 v[36:37], v[0:1], v[34:35] op_sel:[0,1]
	v_lshlrev_b32_e32 v188, 1, v4
	v_pk_fma_f32 v[50:51], v[0:1], v[34:35], v[36:37] op_sel:[1,0,0] op_sel_hi:[0,0,1]
	v_pk_fma_f32 v[36:37], v[0:1], v[34:35], v[36:37] op_sel:[1,0,0] op_sel_hi:[0,0,1] neg_lo:[0,0,1] neg_hi:[0,0,1]
	v_mov_b32_e32 v37, v51
	v_mul_u32_u24_e32 v4, 0x300, v64
	v_pk_add_f32 v[36:37], v[38:39], v[36:37]
	v_lshl_add_u64 v[62:63], v[2:3], 0, v[188:189]
	v_lshlrev_b32_e32 v188, 1, v4
	v_mul_f32_e32 v4, v0, v37
	v_pk_fma_f32 v[38:39], v[0:1], v[36:37], v[4:5] op_sel:[1,0,0] op_sel_hi:[0,1,0] neg_lo:[0,0,1] neg_hi:[0,0,1]
	v_mul_f32_e32 v4, v0, v36
	v_pk_fma_f32 v[50:51], v[0:1], v[36:37], v[4:5] op_sel_hi:[1,1,0]
	v_mul_u32_u24_e32 v4, 0x300, v66
	v_mov_b32_e32 v39, v51
	v_pk_add_f32 v[38:39], v[40:41], v[38:39]
	v_lshl_add_u64 v[64:65], v[2:3], 0, v[188:189]
	v_pk_mul_f32 v[40:41], v[0:1], v[38:39] op_sel:[0,1]
	v_lshlrev_b32_e32 v188, 1, v4
	v_pk_fma_f32 v[50:51], v[0:1], v[38:39], v[40:41] op_sel:[1,0,0] op_sel_hi:[0,1,1] neg_lo:[0,0,1] neg_hi:[0,0,1]
	v_pk_fma_f32 v[40:41], v[0:1], v[38:39], v[40:41] op_sel:[1,0,0] op_sel_hi:[0,0,1]
	v_mov_b32_e32 v51, v41
	v_pk_add_f32 v[22:23], v[22:23], v[50:51]
	v_mul_u32_u24_e32 v4, 0x300, v68
	v_pk_mul_f32 v[40:41], v[0:1], v[22:23] op_sel_hi:[0,1]
	v_pk_fma_f32 v[50:51], v[0:1], v[22:23], v[40:41] op_sel:[0,0,1] op_sel_hi:[1,1,0]
	v_pk_fma_f32 v[40:41], v[0:1], v[22:23], v[40:41] op_sel:[1,0,1] op_sel_hi:[1,1,0] neg_lo:[0,0,1] neg_hi:[0,0,1]
	v_lshl_add_u64 v[66:67], v[2:3], 0, v[188:189]
	v_mov_b32_e32 v41, v51
	v_pk_add_f32 v[40:41], v[44:45], v[40:41]
	v_lshlrev_b32_e32 v188, 1, v4
	v_pk_mul_f32 v[44:45], v[0:1], v[40:41] op_sel_hi:[0,1]
	v_pk_fma_f32 v[50:51], v[0:1], v[40:41], v[44:45] op_sel:[0,0,1] op_sel_hi:[1,1,0]
	v_pk_fma_f32 v[44:45], v[0:1], v[40:41], v[44:45] op_sel:[1,0,1] op_sel_hi:[1,1,0] neg_lo:[0,0,1] neg_hi:[0,0,1]
	v_lshl_add_u64 v[68:69], v[2:3], 0, v[188:189]
	v_mov_b32_e32 v45, v51
	v_pk_add_f32 v[44:45], v[46:47], v[44:45]
	s_nop 0
	v_pk_mul_f32 v[46:47], v[0:1], v[44:45] op_sel_hi:[0,1]
	v_pk_fma_f32 v[50:51], v[0:1], v[44:45], v[46:47] op_sel:[0,0,1] op_sel_hi:[1,1,0]
	v_pk_fma_f32 v[46:47], v[0:1], v[44:45], v[46:47] op_sel:[1,0,1] op_sel_hi:[1,1,0] neg_lo:[0,0,1] neg_hi:[0,0,1]
	s_nop 0
	v_mov_b32_e32 v47, v51
	v_pk_add_f32 v[46:47], v[48:49], v[46:47]
	s_nop 0
	v_pk_mul_f32 v[48:49], v[0:1], v[46:47] op_sel:[1,0] op_sel_hi:[0,1]
	v_sub_f32_e32 v4, v48, v49
	v_pk_mul_f32 v[48:49], v[0:1], v[46:47]
	v_add_f32_e32 v4, v52, v4
	v_add_f32_e32 v15, v49, v48
	v_add_f32_e32 v15, v53, v15
	ds_bpermute_b32 v48, v77, v4
	ds_bpermute_b32 v49, v77, v15
	ds_bpermute_b32 v50, v77, v4 offset:32
	ds_bpermute_b32 v51, v77, v15 offset:32
	ds_bpermute_b32 v52, v77, v4 offset:64
	ds_bpermute_b32 v53, v77, v15 offset:64
	s_waitcnt lgkmcnt(4)
	v_pk_add_f32 v[42:43], v[42:43], v[48:49]
	ds_bpermute_b32 v70, v77, v4 offset:96
	v_pk_mul_f32 v[48:49], v[6:7], v[42:43] op_sel:[1,1] op_sel_hi:[0,1]
	ds_bpermute_b32 v71, v77, v15 offset:96
	ds_bpermute_b32 v72, v77, v4 offset:128
	ds_bpermute_b32 v73, v77, v15 offset:128
	ds_bpermute_b32 v74, v77, v4 offset:160
	ds_bpermute_b32 v75, v77, v15 offset:160
	ds_bpermute_b32 v76, v77, v4 offset:192
	ds_bpermute_b32 v77, v77, v15 offset:192
	v_cndmask_b32_e32 v4, 0, v43, vcc
	v_cndmask_b32_e32 v15, 0, v42, vcc
	v_pk_fma_f32 v[78:79], v[6:7], v[42:43], v[48:49] neg_lo:[0,0,1] neg_hi:[0,0,1]
	v_pk_fma_f32 v[42:43], v[6:7], v[42:43], v[48:49] op_sel_hi:[1,0,1]
	v_cmp_eq_u32_e32 vcc, 2, v14
	v_mov_b32_e32 v79, v43
	s_waitcnt lgkmcnt(10)
	v_pk_add_f32 v[42:43], v[78:79], v[50:51]
	s_nop 0
	v_pk_mul_f32 v[48:49], v[6:7], v[42:43] op_sel:[1,0]
	v_cndmask_b32_e32 v15, v15, v42, vcc
	v_cndmask_b32_e32 v4, v4, v43, vcc
	v_pk_fma_f32 v[50:51], v[6:7], v[42:43], v[48:49] op_sel:[0,0,1] op_sel_hi:[1,1,0] neg_lo:[0,0,1] neg_hi:[0,0,1]
	v_pk_fma_f32 v[42:43], v[6:7], v[42:43], v[48:49] op_sel:[0,0,1] op_sel_hi:[0,1,0]
	v_mov_b32_e32 v51, v43
	s_waitcnt lgkmcnt(8)
	v_pk_add_f32 v[42:43], v[50:51], v[52:53]
	v_cmp_eq_u32_e32 vcc, 3, v14
	v_pk_mul_f32 v[48:49], v[6:7], v[42:43] op_sel:[1,0]
	s_nop 0
	v_cndmask_b32_e32 v4, v4, v43, vcc
	v_cndmask_b32_e32 v15, v15, v42, vcc
	v_pk_fma_f32 v[50:51], v[6:7], v[42:43], v[48:49] op_sel:[0,0,1] op_sel_hi:[1,1,0] neg_lo:[0,0,1] neg_hi:[0,0,1]
	v_pk_fma_f32 v[42:43], v[6:7], v[42:43], v[48:49] op_sel:[0,0,1] op_sel_hi:[0,1,0]
	v_mov_b32_e32 v51, v43
	s_waitcnt lgkmcnt(6)
	v_pk_add_f32 v[42:43], v[50:51], v[70:71]
	v_cmp_eq_u32_e32 vcc, 4, v14
	v_pk_mul_f32 v[48:49], v[6:7], v[42:43] op_sel:[1,0]
	s_nop 0
	v_cndmask_b32_e32 v15, v15, v42, vcc
	v_cndmask_b32_e32 v4, v4, v43, vcc
	v_pk_fma_f32 v[50:51], v[6:7], v[42:43], v[48:49] op_sel:[0,0,1] op_sel_hi:[1,1,0] neg_lo:[0,0,1] neg_hi:[0,0,1]
	v_pk_fma_f32 v[42:43], v[6:7], v[42:43], v[48:49] op_sel:[0,0,1] op_sel_hi:[0,1,0]
	v_mov_b32_e32 v51, v43
	s_waitcnt lgkmcnt(4)
	v_pk_add_f32 v[42:43], v[50:51], v[72:73]
	v_cmp_eq_u32_e32 vcc, 5, v14
	v_pk_mul_f32 v[48:49], v[6:7], v[42:43] op_sel:[1,0]
	s_nop 0
	v_cndmask_b32_e32 v4, v4, v43, vcc
	v_cndmask_b32_e32 v15, v15, v42, vcc
	v_pk_fma_f32 v[50:51], v[6:7], v[42:43], v[48:49] op_sel:[0,0,1] op_sel_hi:[1,1,0] neg_lo:[0,0,1] neg_hi:[0,0,1]
	v_pk_fma_f32 v[42:43], v[6:7], v[42:43], v[48:49] op_sel:[0,0,1] op_sel_hi:[0,1,0]
	v_mov_b32_e32 v51, v43
	s_waitcnt lgkmcnt(2)
; DI float2 cmul(float2 x, float2 y) { return make_float2(x.x * y.x - x.y * y.y, x.x * y.y + x.y * y.x); }
; DI void phase_s5_scan(const Params& P, int layer, int t) {
;     ...
;     for (int m = 0; m < 8; ++m) {
;         if (m == j) mine = C;
;         const float ex = __shfl(H.x, (lane & 0x7) | (m << 3) | (lane & 0x38 & 0) , 64), ey = __shfl(H.y, (lane & 0x7) | (m << 3), 64);
;         const float2 nc = cmul(lt16, C); C = make_float2(nc.x + ex, nc.y + ey);
;     }
	v_pk_add_f32 v[42:43], v[50:51], v[74:75]
	v_cmp_eq_u32_e32 vcc, 6, v14
	v_pk_mul_f32 v[48:49], v[6:7], v[42:43] op_sel:[1,0]
	s_nop 0
	v_pk_fma_f32 v[50:51], v[6:7], v[42:43], v[48:49] op_sel:[0,0,1] op_sel_hi:[1,1,0] neg_lo:[0,0,1] neg_hi:[0,0,1]
	v_pk_fma_f32 v[6:7], v[6:7], v[42:43], v[48:49] op_sel:[0,0,1] op_sel_hi:[0,1,0]
	v_mov_b32_e32 v51, v7
	v_cndmask_b32_e32 v15, v15, v42, vcc
	v_cndmask_b32_e32 v4, v4, v43, vcc
	s_waitcnt lgkmcnt(0)
; DI unsigned pk2(float lo, float hi) { const f32x2_t v = {lo, hi}; return __builtin_bit_cast(unsigned, __builtin_convertvector(v, bf16x2_t)); }
; DI float2 cmul(float2 x, float2 y) { return make_float2(x.x * y.x - x.y * y.y, x.x * y.y + x.y * y.x); }
; DI void phase_s5_scan(const Params& P, int layer, int t) {
;     ...
;     for (int m = 0; m < 8; ++m) {
;         if (m == j) mine = C;
;         const float ex = __shfl(H.x, (lane & 0x7) | (m << 3) | (lane & 0x38 & 0) , 64), ey = __shfl(H.y, (lane & 0x7) | (m << 3), 64);
;         const float2 nc = cmul(lt16, C); C = make_float2(nc.x + ex, nc.y + ey);
;     }
;     float2 W = mine;
; #pragma unroll
;     for (int i = 0; i < 16; ++i) {
;         const int k = 16 * j + i, cidx = d == 0 ? k : NCH - 1 - k;
;         *(unsigned*)(u2 + (size_t)cidx * U2LD) = pk2(W.x + pf[i].x, W.y + pf[i].y);
;         W = cmul(lt, W);
;     }
	v_pk_add_f32 v[6:7], v[50:51], v[76:77]
	v_cmp_eq_u32_e32 vcc, 7, v14
	s_nop 1
	v_cndmask_b32_e32 v7, v4, v7, vcc
	v_cndmask_b32_e32 v6, v15, v6, vcc
	v_pk_add_f32 v[14:15], v[6:7], 0
	s_nop 0
	v_cvt_pk_bf16_f32 v4, v14, v15
	v_pk_mul_f32 v[14:15], v[0:1], v[6:7] op_sel_hi:[0,1]
	global_store_dword v[20:21], v4, off
	v_pk_fma_f32 v[20:21], v[0:1], v[6:7], v[14:15] op_sel:[1,0,1] op_sel_hi:[1,1,0] neg_lo:[0,0,1] neg_hi:[0,0,1]
	v_pk_fma_f32 v[6:7], v[0:1], v[6:7], v[14:15] op_sel:[1,0,1] op_sel_hi:[1,1,0]
	s_nop 0
	v_mov_b32_e32 v21, v7
	v_pk_add_f32 v[6:7], v[10:11], v[20:21]
	s_nop 0
	v_cvt_pk_bf16_f32 v4, v6, v7
	v_pk_mul_f32 v[6:7], v[0:1], v[20:21] op_sel_hi:[0,1]
	v_pk_fma_f32 v[10:11], v[0:1], v[20:21], v[6:7] op_sel:[1,0,1] op_sel_hi:[1,1,0] neg_lo:[0,0,1] neg_hi:[0,0,1]
	v_pk_fma_f32 v[6:7], v[0:1], v[20:21], v[6:7] op_sel:[1,0,1] op_sel_hi:[1,1,0]
	global_store_dword v[54:55], v4, off
	v_mov_b32_e32 v6, v10
	v_pk_add_f32 v[14:15], v[24:25], v[6:7]
	s_nop 0
	v_cvt_pk_bf16_f32 v4, v14, v15
	v_pk_mul_f32 v[14:15], v[0:1], v[6:7] op_sel_hi:[0,1]
	v_pk_fma_f32 v[10:11], v[0:1], v[10:11], v[14:15] op_sel:[1,0,1] op_sel_hi:[1,1,0] neg_lo:[0,0,1] neg_hi:[0,0,1]
	v_pk_fma_f32 v[6:7], v[0:1], v[6:7], v[14:15] op_sel:[1,0,1] op_sel_hi:[1,1,0]
	global_store_dword v[18:19], v4, off
	v_mov_b32_e32 v11, v7
	v_pk_add_f32 v[6:7], v[26:27], v[10:11]
	s_nop 0
	v_cvt_pk_bf16_f32 v4, v6, v7
	v_pk_mul_f32 v[6:7], v[0:1], v[10:11] op_sel_hi:[0,1]
	v_pk_fma_f32 v[14:15], v[0:1], v[10:11], v[6:7] op_sel:[1,0,1] op_sel_hi:[1,1,0] neg_lo:[0,0,1] neg_hi:[0,0,1]
	v_pk_fma_f32 v[6:7], v[0:1], v[10:11], v[6:7] op_sel:[1,0,1] op_sel_hi:[1,1,0]
	global_store_dword v[56:57], v4, off
	v_mov_b32_e32 v6, v14
	v_pk_add_f32 v[8:9], v[8:9], v[6:7]
	s_nop 0
	v_cvt_pk_bf16_f32 v4, v8, v9
	v_pk_mul_f32 v[8:9], v[0:1], v[6:7] op_sel_hi:[0,1]
	v_pk_fma_f32 v[10:11], v[0:1], v[14:15], v[8:9] op_sel:[1,0,1] op_sel_hi:[1,1,0] neg_lo:[0,0,1] neg_hi:[0,0,1]
	v_pk_fma_f32 v[6:7], v[0:1], v[6:7], v[8:9] op_sel:[1,0,1] op_sel_hi:[1,1,0]
	global_store_dword v[16:17], v4, off
	v_mov_b32_e32 v11, v7
	v_pk_add_f32 v[6:7], v[12:13], v[10:11]
	s_nop 0
	v_cvt_pk_bf16_f32 v4, v6, v7
	v_pk_mul_f32 v[6:7], v[0:1], v[10:11] op_sel_hi:[0,1]
	v_pk_fma_f32 v[8:9], v[0:1], v[10:11], v[6:7] op_sel:[1,0,1] op_sel_hi:[1,1,0] neg_lo:[0,0,1] neg_hi:[0,0,1]
	v_pk_fma_f32 v[6:7], v[0:1], v[10:11], v[6:7] op_sel:[1,0,1] op_sel_hi:[1,1,0]
	global_store_dword v[58:59], v4, off
	v_mov_b32_e32 v6, v8
	v_pk_add_f32 v[10:11], v[30:31], v[6:7]
	s_nop 0
	v_cvt_pk_bf16_f32 v4, v10, v11
	v_pk_mul_f32 v[10:11], v[0:1], v[6:7] op_sel_hi:[0,1]
	v_pk_fma_f32 v[8:9], v[0:1], v[8:9], v[10:11] op_sel:[1,0,1] op_sel_hi:[1,1,0] neg_lo:[0,0,1] neg_hi:[0,0,1]
	v_pk_fma_f32 v[6:7], v[0:1], v[6:7], v[10:11] op_sel:[1,0,1] op_sel_hi:[1,1,0]
	global_store_dword v[60:61], v4, off
	v_mov_b32_e32 v9, v7
	v_pk_add_f32 v[6:7], v[28:29], v[8:9]
	s_nop 0
	v_cvt_pk_bf16_f32 v4, v6, v7
	v_pk_mul_f32 v[6:7], v[0:1], v[8:9] op_sel_hi:[0,1]
	v_pk_fma_f32 v[10:11], v[0:1], v[8:9], v[6:7] op_sel:[1,0,1] op_sel_hi:[1,1,0] neg_lo:[0,0,1] neg_hi:[0,0,1]
	v_pk_fma_f32 v[6:7], v[0:1], v[8:9], v[6:7] op_sel:[1,0,1] op_sel_hi:[1,1,0]
	global_store_dword v[62:63], v4, off
	v_mov_b32_e32 v6, v10
	v_pk_add_f32 v[8:9], v[32:33], v[6:7]
	s_nop 0
	v_cvt_pk_bf16_f32 v4, v8, v9
	v_pk_mul_f32 v[8:9], v[0:1], v[6:7] op_sel_hi:[0,1]
	v_pk_fma_f32 v[10:11], v[0:1], v[10:11], v[8:9] op_sel:[1,0,1] op_sel_hi:[1,1,0] neg_lo:[0,0,1] neg_hi:[0,0,1]
	v_pk_fma_f32 v[6:7], v[0:1], v[6:7], v[8:9] op_sel:[1,0,1] op_sel_hi:[1,1,0]
	global_store_dword v[64:65], v4, off
	v_mov_b32_e32 v11, v7
	v_pk_add_f32 v[6:7], v[34:35], v[10:11]
	s_nop 0
	v_cvt_pk_bf16_f32 v4, v6, v7
	v_pk_mul_f32 v[6:7], v[0:1], v[10:11] op_sel_hi:[0,1]
	v_pk_fma_f32 v[8:9], v[0:1], v[10:11], v[6:7] op_sel:[1,0,1] op_sel_hi:[1,1,0] neg_lo:[0,0,1] neg_hi:[0,0,1]
	v_pk_fma_f32 v[6:7], v[0:1], v[10:11], v[6:7] op_sel:[1,0,1] op_sel_hi:[1,1,0]
	global_store_dword v[66:67], v4, off
	v_mov_b32_e32 v6, v8
	v_pk_add_f32 v[10:11], v[36:37], v[6:7]
	s_nop 0
	v_cvt_pk_bf16_f32 v4, v10, v11
	v_pk_mul_f32 v[10:11], v[0:1], v[6:7] op_sel_hi:[0,1]
	v_pk_fma_f32 v[8:9], v[0:1], v[8:9], v[10:11] op_sel:[1,0,1] op_sel_hi:[1,1,0] neg_lo:[0,0,1] neg_hi:[0,0,1]
	v_pk_fma_f32 v[6:7], v[0:1], v[6:7], v[10:11] op_sel:[1,0,1] op_sel_hi:[1,1,0]
	global_store_dword v[68:69], v4, off
	v_mov_b32_e32 v9, v7
	v_pk_add_f32 v[6:7], v[38:39], v[8:9]
	s_nop 0
	v_cvt_pk_bf16_f32 v4, v6, v7
	v_mul_u32_u24_e32 v6, 0x300, v80
	v_lshlrev_b32_e32 v188, 1, v6
	v_lshl_add_u64 v[6:7], v[2:3], 0, v[188:189]
	global_store_dword v[6:7], v4, off
	v_pk_mul_f32 v[6:7], v[0:1], v[8:9] op_sel_hi:[0,1]
	v_pk_fma_f32 v[10:11], v[0:1], v[8:9], v[6:7] op_sel:[1,0,1] op_sel_hi:[1,1,0] neg_lo:[0,0,1] neg_hi:[0,0,1]
	v_pk_fma_f32 v[6:7], v[0:1], v[8:9], v[6:7] op_sel:[1,0,1] op_sel_hi:[1,1,0]
	s_nop 0
	v_mov_b32_e32 v6, v10
	v_pk_add_f32 v[8:9], v[22:23], v[6:7]
	s_nop 0
	v_cvt_pk_bf16_f32 v4, v8, v9
	v_mul_u32_u24_e32 v8, 0x300, v81
	v_lshlrev_b32_e32 v188, 1, v8
	v_lshl_add_u64 v[8:9], v[2:3], 0, v[188:189]
	global_store_dword v[8:9], v4, off
	v_pk_mul_f32 v[8:9], v[0:1], v[6:7] op_sel_hi:[0,1]
	v_pk_fma_f32 v[10:11], v[0:1], v[10:11], v[8:9] op_sel:[1,0,1] op_sel_hi:[1,1,0] neg_lo:[0,0,1] neg_hi:[0,0,1]
	v_pk_fma_f32 v[6:7], v[0:1], v[6:7], v[8:9] op_sel:[1,0,1] op_sel_hi:[1,1,0]
	s_nop 0
	v_mov_b32_e32 v11, v7
	v_pk_add_f32 v[6:7], v[40:41], v[10:11]
	s_nop 0
	v_cvt_pk_bf16_f32 v4, v6, v7
	v_mul_u32_u24_e32 v6, 0x300, v82
	v_lshlrev_b32_e32 v188, 1, v6
	v_lshl_add_u64 v[6:7], v[2:3], 0, v[188:189]
	global_store_dword v[6:7], v4, off
	v_pk_mul_f32 v[6:7], v[0:1], v[10:11] op_sel_hi:[0,1]
	v_pk_fma_f32 v[8:9], v[0:1], v[10:11], v[6:7] op_sel:[1,0,1] op_sel_hi:[1,1,0] neg_lo:[0,0,1] neg_hi:[0,0,1]
	v_pk_fma_f32 v[6:7], v[0:1], v[10:11], v[6:7] op_sel:[1,0,1] op_sel_hi:[1,1,0]
	s_nop 0
	v_mov_b32_e32 v6, v8
	v_pk_add_f32 v[10:11], v[44:45], v[6:7]
	s_nop 0
	v_cvt_pk_bf16_f32 v4, v10, v11
	v_mul_u32_u24_e32 v10, 0x300, v83
	v_lshlrev_b32_e32 v188, 1, v10
	v_lshl_add_u64 v[10:11], v[2:3], 0, v[188:189]
	global_store_dword v[10:11], v4, off
	v_pk_mul_f32 v[10:11], v[0:1], v[6:7] op_sel_hi:[0,1]
	v_pk_fma_f32 v[8:9], v[0:1], v[8:9], v[10:11] op_sel:[1,0,1] op_sel_hi:[1,1,0] neg_lo:[0,0,1] neg_hi:[0,0,1]
	v_pk_fma_f32 v[0:1], v[0:1], v[6:7], v[10:11] op_sel:[1,0,1] op_sel_hi:[1,1,0]
	s_nop 0
	v_mov_b32_e32 v9, v1
	v_pk_add_f32 v[0:1], v[46:47], v[8:9]
	s_nop 0
	v_cvt_pk_bf16_f32 v4, v0, v1
	v_mul_u32_u24_e32 v0, 0x300, v84
	v_lshlrev_b32_e32 v188, 1, v0
	v_lshl_add_u64 v[0:1], v[2:3], 0, v[188:189]
	global_store_dword v[0:1], v4, off

; DI void flat_barrier(unsigned char* wsb, LAS unsigned char* ldsb) {
;     ...
;         __builtin_amdgcn_fence(__ATOMIC_ACQUIRE, "agent");
;         asm volatile("s_waitcnt vmcnt(0)" ::: "memory");
;     }
;     __syncthreads();
.Lnb_acq2:
	buffer_inv sc1
	s_waitcnt vmcnt(0)
.LBB0_1204:
	s_or_b64 exec, exec, s[6:7]
	s_mov_b32 s7, s94
	v_mov_b32_e32 v14, v232
	s_barrier
	s_and_b64 vcc, exec, s[12:13]
	v_readfirstlane_b32 s2, v14
	s_cbranch_vccnz .LBB0_1226
	s_and_b64 vcc, exec, s[10:11]
	v_readlane_b32 s6, v254, 3
	s_cbranch_vccnz .LBB0_1207
	v_readlane_b32 s6, v253, 50

; #define LAS __attribute__((address_space(3)))
; DI int opq0() { int z = 0; asm volatile("" : "+s"(z)); return z; }
; DI int tid_opq() { int t = threadIdx.x; asm volatile("" : "+v"(t)); return t; }
; DI unsigned xb_ld(unsigned* p)              { return __hip_atomic_load(p, __ATOMIC_RELAXED, __HIP_MEMORY_SCOPE_AGENT); }
; DI unsigned xb_add(unsigned* p, unsigned v) { return __hip_atomic_fetch_add(p, v, __ATOMIC_RELAXED, __HIP_MEMORY_SCOPE_AGENT); }
; DI void flat_barrier(unsigned char* wsb, LAS unsigned char* ldsb) {
;     asm volatile("s_waitcnt vmcnt(0)" ::: "memory");
;     __syncthreads();
;     if (tid_opq() == 0) {
;         unsigned* cnt = (unsigned*)(wsb + opq0() + WS_BAR) + 64;
;         const unsigned G = gridDim.x;
;         __builtin_amdgcn_fence(__ATOMIC_RELEASE, "agent");
;         asm volatile("s_waitcnt vmcnt(0)" ::: "memory");
;         volatile LAS unsigned* st = (volatile LAS unsigned*)(ldsb + 131072);
;         const unsigned k = st[0] + 1u; st[0] = k;
;         (void)xb_add(cnt, 1u);
;         const unsigned target = k * G;
;         unsigned sp = 0u;
;         while (xb_ld(cnt) < target) { __builtin_amdgcn_s_sleep(1); if (++sp > (1u << 24)) break; }
.LBB0_1319:
	s_waitcnt vmcnt(0)
	v_mov_b32_e32 v0, v232
	s_waitcnt lgkmcnt(0)
	s_barrier
	s_nop 0
	v_cmp_gt_u32_e32 vcc, 16, v0
	s_and_saveexec_b64 s[6:7], vcc
	s_cbranch_execz .LBB0_1336
	buffer_wbl2 sc1
	s_waitcnt vmcnt(0)
	v_readlane_b32 s0, v254, 34
	v_readlane_b32 s8, v254, 31
	v_readlane_b32 s9, v254, 32
	v_readlane_b32 s2, v255, 9
	s_nop 3
	v_mov_b32_e32 v0, s0
	ds_read_b32 v1, v0
	s_add_u32 s8, s8, s94
	s_addc_u32 s9, s9, 0
	s_add_u32 s8, s8, 0x1e002000
	s_addc_u32 s9, s9, 0
	s_and_b32 s2, s2, 15
	s_lshl_b32 s2, s2, 7
	s_waitcnt lgkmcnt(0)
	v_add_u32_e32 v1, 1, v1
	ds_write_b32 v0, v1
	s_waitcnt lgkmcnt(0)
	v_readfirstlane_b32 s0, v1
	s_mov_b64 vcc, exec
	s_mov_b64 exec, 1
	v_mov_b32_e32 v0, s2
	v_mov_b32_e32 v1, 1
	global_atomic_add v0, v1, s[8:9]
	s_mov_b64 exec, vcc
	s_add_u32 s2, s58, 15
	v_sub_u32_e32 v0, s2, v232
	v_lshrrev_b32_e32 v0, 4, v0
	v_mul_lo_u32 v0, v0, s0
	s_mov_b32 s2, 0x4000

; DI void flat_barrier(unsigned char* wsb, LAS unsigned char* ldsb) {
;     ...
;         __builtin_amdgcn_fence(__ATOMIC_ACQUIRE, "agent");
;         asm volatile("s_waitcnt vmcnt(0)" ::: "memory");
;     }
;     __syncthreads();
.Lnb_acq3:
	buffer_inv sc1
	s_waitcnt vmcnt(0)
.LBB0_1336:
	s_or_b64 exec, exec, s[6:7]
	v_readlane_b32 s8, v253, 57
	s_mov_b32 s7, s94
	v_mov_b32_e32 v14, v232
	v_readlane_b32 s9, v253, 58
	s_barrier
	s_andn2_b64 vcc, exec, s[8:9]
	v_readfirstlane_b32 s2, v14
	s_cbranch_vccnz .LBB0_1358
	v_readlane_b32 s8, v254, 4
	v_readlane_b32 s9, v254, 5
	s_andn2_b64 vcc, exec, s[8:9]
	v_readlane_b32 s6, v254, 7
	s_cbranch_vccnz .LBB0_1339
	v_readlane_b32 s6, v254, 6

; #define LAS __attribute__((address_space(3)))
; DI int opq0() { int z = 0; asm volatile("" : "+s"(z)); return z; }
; DI int tid_opq() { int t = threadIdx.x; asm volatile("" : "+v"(t)); return t; }
; DI unsigned xb_ld(unsigned* p)              { return __hip_atomic_load(p, __ATOMIC_RELAXED, __HIP_MEMORY_SCOPE_AGENT); }
; DI unsigned xb_add(unsigned* p, unsigned v) { return __hip_atomic_fetch_add(p, v, __ATOMIC_RELAXED, __HIP_MEMORY_SCOPE_AGENT); }
; DI void flat_barrier(unsigned char* wsb, LAS unsigned char* ldsb) {
;     asm volatile("s_waitcnt vmcnt(0)" ::: "memory");
;     __syncthreads();
;     if (tid_opq() == 0) {
;         unsigned* cnt = (unsigned*)(wsb + opq0() + WS_BAR) + 64;
;         const unsigned G = gridDim.x;
;         __builtin_amdgcn_fence(__ATOMIC_RELEASE, "agent");
;         asm volatile("s_waitcnt vmcnt(0)" ::: "memory");
;         volatile LAS unsigned* st = (volatile LAS unsigned*)(ldsb + 131072);
;         const unsigned k = st[0] + 1u; st[0] = k;
;         (void)xb_add(cnt, 1u);
;         const unsigned target = k * G;
;         unsigned sp = 0u;
;         while (xb_ld(cnt) < target) { __builtin_amdgcn_s_sleep(1); if (++sp > (1u << 24)) break; }
.LBB0_1370:
	s_waitcnt vmcnt(0)
	v_mov_b32_e32 v0, v232
	s_barrier
	s_nop 0
	v_cmp_gt_u32_e32 vcc, 16, v0
	s_and_saveexec_b64 s[6:7], vcc
	s_cbranch_execz .LBB0_1387
	buffer_wbl2 sc1
	s_waitcnt vmcnt(0)
	v_readlane_b32 s0, v254, 34
	v_readlane_b32 s8, v254, 31
	v_readlane_b32 s9, v254, 32
	v_readlane_b32 s2, v255, 9
	s_nop 3
	v_mov_b32_e32 v0, s0
	ds_read_b32 v1, v0
	s_add_u32 s8, s8, s94
	s_addc_u32 s9, s9, 0
	s_add_u32 s8, s8, 0x1e002000
	s_addc_u32 s9, s9, 0
	s_and_b32 s2, s2, 15
	s_lshl_b32 s2, s2, 7
	s_waitcnt lgkmcnt(0)
	v_add_u32_e32 v1, 1, v1
	ds_write_b32 v0, v1
	s_waitcnt lgkmcnt(0)
	v_readfirstlane_b32 s0, v1
	s_mov_b64 vcc, exec
	s_mov_b64 exec, 1
	v_mov_b32_e32 v0, s2
	v_mov_b32_e32 v1, 1
	global_atomic_add v0, v1, s[8:9]
	s_mov_b64 exec, vcc
	s_add_u32 s2, s58, 15
	v_sub_u32_e32 v0, s2, v232
	v_lshrrev_b32_e32 v0, 4, v0
	v_mul_lo_u32 v0, v0, s0
	s_mov_b32 s2, 0x4000

; DI void flat_barrier(unsigned char* wsb, LAS unsigned char* ldsb) {
;     ...
;         __builtin_amdgcn_fence(__ATOMIC_ACQUIRE, "agent");
;         asm volatile("s_waitcnt vmcnt(0)" ::: "memory");
;     }
;     __syncthreads();
.Lnb_acq4:
	buffer_inv sc1
	s_waitcnt vmcnt(0)
.LBB0_1387:
	s_or_b64 exec, exec, s[6:7]
	s_mov_b32 s20, s94
	v_mov_b32_e32 v14, v232
	s_barrier
	s_and_b64 vcc, exec, s[12:13]
	v_readfirstlane_b32 s2, v14
	s_cbranch_vccz .LBB0_1390
	s_andn2_b64 vcc, exec, s[14:15]
	s_cbranch_vccz .LBB0_1411

; DI void flat_barrier(unsigned char* wsb, LAS unsigned char* ldsb) {
;     ...
;         __builtin_amdgcn_fence(__ATOMIC_ACQUIRE, "agent");
;         asm volatile("s_waitcnt vmcnt(0)" ::: "memory");
;     }
;     __syncthreads();
.Lnb_acq5:
	buffer_inv sc1
	s_waitcnt vmcnt(0)
.LBB0_1428:
	s_or_b64 exec, exec, s[6:7]
	s_barrier
	s_cmp_eq_u32 s35, 3
	s_cbranch_scc0 .LBB0_1429
	s_getpc_b64 s[98:99]
